# attention QK^T (in-loop sections): K-fragment LDS reads issued one step further ahead using two extra fragment registers (v248-v255); counted lgkm waits re-derived
# baseline (speedup 1.0000x reference)
; #define SBAR() __builtin_amdgcn_sched_barrier(0)
; __device__ __forceinline__ void finishSM(f32x16& p0, f32x16& p1, float alpha, float& l_reg, bf16x8& pa0, bf16x8& pa1, bf16x8& pa2, bf16x8& pa3) {
; #pragma unroll
;   for (int r = 0; r < 16; ++r) p1[r] = __builtin_amdgcn_exp2f(p1[r]);
;   float ps = 0;
; #pragma unroll
;   for (int r = 0; r < 16; ++r) ps += p0[r];
; #pragma unroll
;   for (int r = 0; r < 16; ++r) ps += p1[r];
;   { auto rr = __builtin_amdgcn_permlane32_swap(__float_as_uint(ps), __float_as_uint(ps), false, false);
;     ps = __uint_as_float(rr[0]) + __uint_as_float(rr[1]); }
;   l_reg = l_reg * alpha + ps;
;     ...
;   PK4(p0, 0, pa0); PK4(p0, 8, pa1); PK4(p1, 0, pa2); PK4(p1, 8, pa3);
;     ...
; }
; __device__ __forceinline__ void qkt(f32x16& p0, f32x16& p1, const bf16_t* Ks, const bf16x8* qr, int r32, int hi) {
;   p0 = f32x16{}; p1 = f32x16{};
; #pragma unroll
;   for (int d0 = 0; d0 < 8; ++d0) { int cb = (d0 * 16 + hi * 8) * 2;
;     bf16x8 b0 = *reinterpret_cast<const bf16x8*>((const char*)Ks + KSWZ(r32, cb));
;     bf16x8 b1 = *reinterpret_cast<const bf16x8*>((const char*)Ks + KSWZ(32 + r32, cb));
;     p0 = __builtin_amdgcn_mfma_f32_32x32x16_bf16(b0, qr[d0], p0, 0, 0, 0);
;     p1 = __builtin_amdgcn_mfma_f32_32x32x16_bf16(b1, qr[d0], p1, 0, 0, 0); }
; template <int D0> __device__ __forceinline__ void pv_one(f32x16& od, int vb, bf16x8 pa0, bf16x8 pa1, bf16x8 pa2, bf16x8 pa3) {
;   const s16x4 l0 = tr_read<v_rd_off(D0, 0, 0)>(vb), h0 = tr_read<v_rd_off(D0, 0, 1)>(vb), l1 = tr_read<v_rd_off(D0, 1, 0)>(vb), h1 = tr_read<v_rd_off(D0, 1, 1)>(vb);
;   const s16x4 l2 = tr_read<v_rd_off(D0, 2, 0)>(vb), h2 = tr_read<v_rd_off(D0, 2, 1)>(vb), l3 = tr_read<v_rd_off(D0, 3, 0)>(vb), h3 = tr_read<v_rd_off(D0, 3, 1)>(vb);
;   asm volatile("s_waitcnt lgkmcnt(0)" ::: "memory"); SBAR();
.LBB0_444:
	ds_read_b128 v[64:67], v204 offset:49152
	ds_read_b128 v[68:71], v204 offset:57344
	ds_read_b128 v[218:221], v205 offset:49152
	ds_read_b128 v[222:225], v205 offset:57344
	ds_read_b128 v[248:251], v206 offset:49152
	ds_read_b128 v[252:255], v206 offset:57344
	v_add_f32_e32 v161, 0, v175
	v_add_f32_e32 v161, v191, v161
	s_waitcnt lgkmcnt(5)
	v_mfma_f32_32x32x16_bf16 v[80:95], v[64:67], v[124:127], 0
	v_add_f32_e32 v161, v173, v161
	v_add_f32_e32 v161, v190, v161
	v_add_f32_e32 v161, v172, v161
	v_add_f32_e32 v161, v174, v161
	v_add_f32_e32 v161, v170, v161
	v_add_f32_e32 v161, v171, v161
	v_add_f32_e32 v161, v167, v161
	s_waitcnt lgkmcnt(4)
	v_mfma_f32_32x32x16_bf16 v[64:79], v[68:71], v[124:127], 0
	v_add_f32_e32 v161, v169, v161
	v_add_f32_e32 v161, v166, v161
	v_add_f32_e32 v161, v168, v161
	v_exp_f32_e32 v154, v154
	v_add_f32_e32 v161, v163, v161
	v_exp_f32_e32 v155, v155
	v_add_f32_e32 v161, v165, v161
	s_waitcnt lgkmcnt(3)
	v_mfma_f32_32x32x16_bf16 v[80:95], v[218:221], v[120:123], v[80:95]
	v_exp_f32_e32 v152, v152
	v_add_f32_e32 v161, v162, v161
	v_exp_f32_e32 v153, v153
	v_add_f32_e32 v161, v164, v161
	v_exp_f32_e32 v148, v148
	v_add_f32_e32 v161, v154, v161
	v_exp_f32_e32 v149, v149
	s_waitcnt lgkmcnt(2)
	v_mfma_f32_32x32x16_bf16 v[64:79], v[222:225], v[120:123], v[64:79]
	ds_read_b128 v[218:221], v207 offset:49152
	ds_read_b128 v[222:225], v207 offset:57344
	v_add_f32_e32 v161, v155, v161
	v_exp_f32_e32 v146, v146
	v_add_f32_e32 v161, v152, v161
	v_exp_f32_e32 v147, v147
	v_add_f32_e32 v161, v153, v161
	v_exp_f32_e32 v144, v144
	s_waitcnt lgkmcnt(3)
	v_mfma_f32_32x32x16_bf16 v[80:95], v[248:251], v[116:119], v[80:95]
	v_add_f32_e32 v161, v148, v161
	v_exp_f32_e32 v145, v145
	v_add_f32_e32 v161, v149, v161
	v_exp_f32_e32 v158, v158
	v_add_f32_e32 v161, v146, v161
	v_exp_f32_e32 v159, v159
	v_add_f32_e32 v161, v147, v161
	s_waitcnt lgkmcnt(2)
	v_mfma_f32_32x32x16_bf16 v[64:79], v[252:255], v[116:119], v[64:79]
	ds_read_b128 v[248:251], v208 offset:49152
	ds_read_b128 v[252:255], v208 offset:57344
	v_exp_f32_e32 v156, v156
	v_add_f32_e32 v161, v144, v161
	v_exp_f32_e32 v157, v157
	v_add_f32_e32 v161, v145, v161
	v_exp_f32_e32 v150, v150
	v_add_f32_e32 v161, v158, v161
	s_waitcnt lgkmcnt(3)
	v_mfma_f32_32x32x16_bf16 v[80:95], v[218:221], v[112:115], v[80:95]
	v_exp_f32_e32 v151, v151
	v_add_f32_e32 v161, v159, v161
	v_add_f32_e32 v161, v156, v161
	v_add_f32_e32 v161, v157, v161
	v_add_f32_e32 v161, v150, v161
	v_add_f32_e32 v215, v151, v161
	s_waitcnt lgkmcnt(2)
	v_mfma_f32_32x32x16_bf16 v[64:79], v[222:225], v[112:115], v[64:79]
	ds_read_b128 v[218:221], v209 offset:49152
	ds_read_b128 v[222:225], v209 offset:57344
	s_waitcnt lgkmcnt(3)
	v_mfma_f32_32x32x16_bf16 v[80:95], v[248:251], v[108:111], v[80:95]
	s_waitcnt lgkmcnt(2)
	v_mfma_f32_32x32x16_bf16 v[64:79], v[252:255], v[108:111], v[64:79]
	ds_read_b128 v[248:251], v210 offset:49152
	ds_read_b128 v[252:255], v210 offset:57344
	s_waitcnt lgkmcnt(3)
	v_mfma_f32_32x32x16_bf16 v[80:95], v[218:221], v[104:107], v[80:95]
	s_waitcnt lgkmcnt(2)
	v_mfma_f32_32x32x16_bf16 v[64:79], v[222:225], v[104:107], v[64:79]
	ds_read_b128 v[218:221], v211 offset:49152
	ds_read_b128 v[222:225], v211 offset:57344
	s_waitcnt lgkmcnt(3)
	v_mfma_f32_32x32x16_bf16 v[80:95], v[248:251], v[100:103], v[80:95]
	s_waitcnt lgkmcnt(2)
	v_mfma_f32_32x32x16_bf16 v[64:79], v[252:255], v[100:103], v[64:79]
	s_waitcnt lgkmcnt(1)
	v_mfma_f32_32x32x16_bf16 v[80:95], v[218:221], v[96:99], v[80:95]
	v_mov_b32_e32 v218, v215
	s_nop 1
	v_permlane32_swap_b32_e32 v215, v218
	v_cvt_pk_bf16_f32 v220, v175, v191
	v_cvt_pk_bf16_f32 v221, v173, v190
	s_waitcnt lgkmcnt(0)
	v_mfma_f32_32x32x16_bf16 v[64:79], v[222:225], v[96:99], v[64:79]
	v_cvt_pk_bf16_f32 v222, v172, v174
	v_cvt_pk_bf16_f32 v223, v170, v171
	v_cvt_pk_bf16_f32 v170, v167, v169
	v_cvt_pk_bf16_f32 v171, v166, v168
	v_cvt_pk_bf16_f32 v172, v163, v165
	v_cvt_pk_bf16_f32 v173, v162, v164
	v_cvt_pk_bf16_f32 v162, v154, v155
	v_cvt_pk_bf16_f32 v163, v152, v153
	v_cvt_pk_bf16_f32 v164, v148, v149
	v_cvt_pk_bf16_f32 v165, v146, v147
	v_cvt_pk_bf16_f32 v166, v144, v145
	v_cvt_pk_bf16_f32 v167, v158, v159
	v_cvt_pk_bf16_f32 v168, v156, v157
	v_cvt_pk_bf16_f32 v169, v150, v151
	s_nop 0
	v_permlane32_swap_b32_e32 v220, v222
	v_permlane32_swap_b32_e32 v221, v223
	v_permlane32_swap_b32_e32 v170, v172
	v_permlane32_swap_b32_e32 v171, v173
	v_permlane32_swap_b32_e32 v162, v164
	v_permlane32_swap_b32_e32 v163, v165
	v_permlane32_swap_b32_e32 v166, v168
	v_permlane32_swap_b32_e32 v167, v169
	v_lshl_add_u64 v[192:193], s[18:19], 0, v[180:181]
	v_add_co_u32_e32 v144, vcc, s68, v192
	v_lshl_add_u64 v[190:191], s[18:19], 0, v[182:183]
	s_nop 0
	v_addc_co_u32_e32 v145, vcc, 0, v193, vcc
	v_add_co_u32_e32 v148, vcc, s68, v190
	s_nop 1
	v_addc_co_u32_e32 v149, vcc, 0, v191, vcc
	v_add_co_u32_e32 v152, vcc, s69, v192
	global_load_dwordx4 v[144:147], v[144:145], off
	s_nop 0
	global_load_dwordx4 v[148:151], v[148:149], off
	v_addc_co_u32_e32 v153, vcc, 0, v193, vcc
	v_add_co_u32_e32 v156, vcc, s69, v190
	s_nop 1
	v_addc_co_u32_e32 v157, vcc, 0, v191, vcc
	global_load_dwordx4 v[152:155], v[152:153], off
	s_nop 0
	global_load_dwordx4 v[156:159], v[156:157], off
	ds_read_b64_tr_b16 v[224:225], v196 offset:0
	ds_read_b64_tr_b16 v[226:227], v196 offset:0x800
	ds_read_b64_tr_b16 v[228:229], v196 offset:0x1000
	ds_read_b64_tr_b16 v[230:231], v196 offset:0x1800
	ds_read_b64_tr_b16 v[232:233], v196 offset:0x200
	ds_read_b64_tr_b16 v[234:235], v196 offset:0xa00
	ds_read_b64_tr_b16 v[236:237], v196 offset:0x1200
	ds_read_b64_tr_b16 v[238:239], v196 offset:0x1a00
	s_waitcnt lgkmcnt(0)
; __device__ __forceinline__ void partialSM(f32x16& p0, f32x16& p1, float& m_reg, float& mn, float& alpha) {
;   constexpr float C = SCALE * 1.4426950408889634f;
;   float pmax = p0[0];
; #pragma unroll
;   for (int r = 1; r < 16; ++r) pmax = fmaxf(pmax, p0[r]);
; #pragma unroll
;   for (int r = 0; r < 16; ++r) pmax = fmaxf(pmax, p1[r]);
;   { auto rr = __builtin_amdgcn_permlane32_swap(__float_as_uint(pmax), __float_as_uint(pmax), false, false);
;     pmax = fmaxf(__uint_as_float(rr[0]), __uint_as_float(rr[1])); }
; template <int DA, int DB> __device__ __forceinline__ void pv_pair(f32x16& oa, f32x16& ob, int vb, bf16x8 pa0, bf16x8 pa1, bf16x8 pa2, bf16x8 pa3) {
;     ...
;   { const s16x4 al0 = tr_read<v_rd_off(DA, 0, 0)>(vb), ah0 = tr_read<v_rd_off(DA, 0, 1)>(vb), al1 = tr_read<v_rd_off(DA, 1, 0)>(vb), ah1 = tr_read<v_rd_off(DA, 1, 1)>(vb);
;     const s16x4 bl0 = tr_read<v_rd_off(DB, 0, 0)>(vb), bh0 = tr_read<v_rd_off(DB, 0, 1)>(vb), bl1 = tr_read<v_rd_off(DB, 1, 0)>(vb), bh1 = tr_read<v_rd_off(DB, 1, 1)>(vb);
;     asm volatile("s_waitcnt lgkmcnt(0)" ::: "memory"); SBAR();
;     oa = __builtin_amdgcn_mfma_f32_32x32x16_bf16(pa0, PK(al0, ah0), oa, 0, 0, 0); ob = __builtin_amdgcn_mfma_f32_32x32x16_bf16(pa0, PK(bl0, bh0), ob, 0, 0, 0);
;     oa = __builtin_amdgcn_mfma_f32_32x32x16_bf16(pa1, PK(al1, ah1), oa, 0, 0, 0); ob = __builtin_amdgcn_mfma_f32_32x32x16_bf16(pa1, PK(bl1, bh1), ob, 0, 0, 0); }
;   { const s16x4 al2 = tr_read<v_rd_off(DA, 2, 0)>(vb), ah2 = tr_read<v_rd_off(DA, 2, 1)>(vb), al3 = tr_read<v_rd_off(DA, 3, 0)>(vb), ah3 = tr_read<v_rd_off(DA, 3, 1)>(vb);
;     const s16x4 bl2 = tr_read<v_rd_off(DB, 2, 0)>(vb), bh2 = tr_read<v_rd_off(DB, 2, 1)>(vb), bl3 = tr_read<v_rd_off(DB, 3, 0)>(vb), bh3 = tr_read<v_rd_off(DB, 3, 1)>(vb);
;     asm volatile("s_waitcnt lgkmcnt(0)" ::: "memory"); SBAR();
;     oa = __builtin_amdgcn_mfma_f32_32x32x16_bf16(pa2, PK(al2, ah2), oa, 0, 0, 0); ob = __builtin_amdgcn_mfma_f32_32x32x16_bf16(pa2, PK(bl2, bh2), ob, 0, 0, 0);
;     oa = __builtin_amdgcn_mfma_f32_32x32x16_bf16(pa3, PK(al3, ah3), oa, 0, 0, 0); ob = __builtin_amdgcn_mfma_f32_32x32x16_bf16(pa3, PK(bl3, bh3), ob, 0, 0, 0); }
;     ...
; }
; __device__ __forceinline__ void pv_d0(f32x16* o, int vb, bf16x8 pa0, bf16x8 pa1, bf16x8 pa2, bf16x8 pa3) {
;   pv_pair<0, 1>(o[0], o[1], vb, pa0, pa1, pa2, pa3); pv_pair<2, 3>(o[2], o[3], vb, pa0, pa1, pa2, pa3);
	s_nop 0
	v_mfma_f32_32x32x16_bf16 v[0:15], v[220:223], v[224:227], v[0:15]
	ds_read_b64_tr_b16 v[224:225], v196 offset:0x2000
	ds_read_b64_tr_b16 v[226:227], v196 offset:0x2800
	v_mfma_f32_32x32x16_bf16 v[48:63], v[220:223], v[232:235], v[48:63]
	v_mfma_f32_32x32x16_bf16 v[0:15], v[170:173], v[228:231], v[0:15]
	ds_read_b64_tr_b16 v[228:229], v196 offset:0x3000
	ds_read_b64_tr_b16 v[230:231], v196 offset:0x3800
	ds_read_b64_tr_b16 v[232:233], v196 offset:0x2200
	ds_read_b64_tr_b16 v[234:235], v196 offset:0x2a00
	ds_read_b64_tr_b16 v[240:241], v196 offset:0x3200
	ds_read_b64_tr_b16 v[242:243], v196 offset:0x3a00
	s_waitcnt lgkmcnt(0)
	v_mfma_f32_32x32x16_bf16 v[48:63], v[170:173], v[236:239], v[48:63]
	v_mfma_f32_32x32x16_bf16 v[0:15], v[162:165], v[224:227], v[0:15]
	ds_read_b64_tr_b16 v[224:225], v196 offset:0x400
	ds_read_b64_tr_b16 v[226:227], v196 offset:0xc00
	v_mfma_f32_32x32x16_bf16 v[48:63], v[162:165], v[232:235], v[48:63]
	v_mfma_f32_32x32x16_bf16 v[0:15], v[166:169], v[228:231], v[0:15]
	ds_read_b64_tr_b16 v[228:229], v196 offset:0x1400
	ds_read_b64_tr_b16 v[230:231], v196 offset:0x1c00
	ds_read_b64_tr_b16 v[232:233], v196 offset:0x600
	ds_read_b64_tr_b16 v[234:235], v196 offset:0xe00
	ds_read_b64_tr_b16 v[236:237], v196 offset:0x1600
	ds_read_b64_tr_b16 v[238:239], v196 offset:0x1e00
	s_waitcnt lgkmcnt(0)
	v_mfma_f32_32x32x16_bf16 v[48:63], v[166:169], v[240:243], v[48:63]
	v_mfma_f32_32x32x16_bf16 v[32:47], v[220:223], v[224:227], v[32:47]
	v_mfma_f32_32x32x16_bf16 v[16:31], v[220:223], v[232:235], v[16:31]
	ds_read_b64_tr_b16 v[220:221], v196 offset:0x2400
	ds_read_b64_tr_b16 v[222:223], v196 offset:0x2c00
	ds_read_b64_tr_b16 v[224:225], v196 offset:0x3400
	ds_read_b64_tr_b16 v[226:227], v196 offset:0x3c00
	v_mfma_f32_32x32x16_bf16 v[32:47], v[170:173], v[228:231], v[32:47]
	ds_read_b64_tr_b16 v[228:229], v196 offset:0x2600
	ds_read_b64_tr_b16 v[230:231], v196 offset:0x2e00
	ds_read_b64_tr_b16 v[232:233], v196 offset:0x3600
	ds_read_b64_tr_b16 v[234:235], v196 offset:0x3e00
	s_waitcnt lgkmcnt(0)
	v_mfma_f32_32x32x16_bf16 v[16:31], v[170:173], v[236:239], v[16:31]
	v_max_f32_e32 v161, v81, v81
	v_max_f32_e32 v170, v80, v80
	v_max_f32_e32 v161, v170, v161
	v_max3_f32 v161, v161, v82, v83
	v_max3_f32 v161, v161, v84, v85
	v_max3_f32 v161, v161, v86, v87
	v_max3_f32 v161, v161, v88, v89
	v_max3_f32 v161, v161, v90, v91
	v_max3_f32 v161, v161, v92, v93
	v_max3_f32 v161, v161, v94, v95
	v_max3_f32 v161, v161, v64, v65
	v_max3_f32 v161, v161, v66, v67
	v_max3_f32 v161, v161, v68, v69
	v_max3_f32 v161, v161, v70, v71
	v_max3_f32 v161, v161, v72, v73
	v_mfma_f32_32x32x16_bf16 v[32:47], v[162:165], v[220:223], v[32:47]
	v_max3_f32 v161, v161, v74, v75
	v_max3_f32 v161, v161, v76, v77
	v_max3_f32 v161, v161, v78, v79
	s_barrier
	s_waitcnt vmcnt(4)
	v_mfma_f32_32x32x16_bf16 v[16:31], v[162:165], v[228:231], v[16:31]
	v_mov_b32_e32 v162, v161
	s_nop 1
	v_permlane32_swap_b32_e32 v161, v162
	v_max_f32_e32 v162, v162, v162
	v_max_f32_e32 v161, v161, v161
	v_max_f32_e32 v161, v161, v162
	v_max_f32_e32 v163, v160, v160
	v_sub_f32_e32 v162, v161, v160
	v_max_f32_e32 v161, v163, v161
	v_mfma_f32_32x32x16_bf16 v[32:47], v[166:169], v[224:227], v[32:47]
	v_sub_f32_e32 v163, v160, v161
	v_mul_f32_e32 v163, 0x3e0293ee, v163
	v_exp_f32_e32 v163, v163
	v_cmp_ge_f32_e32 vcc, s67, v162
	s_cmp_eq_u64 vcc, exec
	s_cselect_b64 s[6:7], -1, 0
	v_cndmask_b32_e64 v219, v163, 1.0, s[6:7]
	v_mfma_f32_32x32x16_bf16 v[16:31], v[166:169], v[232:235], v[16:31]
	v_cmp_gt_f32_e32 vcc, 1.0, v219
	s_waitcnt vmcnt(4)
	ds_write_b128 v200, v[128:131]
	ds_write_b128 v201, v[132:135]
	ds_write_b128 v202, v[136:139] offset:32768
	ds_write_b128 v203, v[140:143] offset:32768
	s_cbranch_vccz .LBB0_448
	s_and_saveexec_b64 s[20:21], s[4:5]
	ds_write_b32 v198, v219 offset:128
	s_or_b64 exec, exec, s[20:21]
	s_waitcnt lgkmcnt(0)
	v_add_u32_e32 v174, v195, v197
	ds_read_b128 v[162:165], v174 offset:224
	ds_read_b128 v[166:169], v174 offset:192
	ds_read_b128 v[170:173], v174 offset:160
	ds_read_b128 v[220:223], v174 offset:128
	s_waitcnt lgkmcnt(3)
	v_pk_mul_f32 v[12:13], v[12:13], v[162:163]
	s_waitcnt lgkmcnt(2)
	v_pk_mul_f32 v[8:9], v[8:9], v[166:167]
	s_waitcnt lgkmcnt(1)
	v_pk_mul_f32 v[4:5], v[4:5], v[170:171]
	v_pk_mul_f32 v[14:15], v[14:15], v[164:165]
	v_pk_mul_f32 v[10:11], v[10:11], v[168:169]
	v_pk_mul_f32 v[6:7], v[6:7], v[172:173]
	s_waitcnt lgkmcnt(0)
	v_pk_mul_f32 v[2:3], v[2:3], v[222:223]
	v_pk_mul_f32 v[0:1], v[0:1], v[220:221]
	v_pk_mul_f32 v[60:61], v[60:61], v[162:163]
	v_pk_mul_f32 v[56:57], v[56:57], v[166:167]
	v_pk_mul_f32 v[52:53], v[52:53], v[170:171]
	v_pk_mul_f32 v[62:63], v[62:63], v[164:165]
	v_pk_mul_f32 v[58:59], v[58:59], v[168:169]
	v_pk_mul_f32 v[54:55], v[54:55], v[172:173]
	v_pk_mul_f32 v[50:51], v[50:51], v[222:223]
	v_pk_mul_f32 v[48:49], v[48:49], v[220:221]
	v_pk_mul_f32 v[44:45], v[44:45], v[162:163]
	v_pk_mul_f32 v[40:41], v[40:41], v[166:167]
	v_pk_mul_f32 v[36:37], v[36:37], v[170:171]
	v_pk_mul_f32 v[46:47], v[46:47], v[164:165]
	v_pk_mul_f32 v[42:43], v[42:43], v[168:169]
	v_pk_mul_f32 v[38:39], v[38:39], v[172:173]
	v_pk_mul_f32 v[34:35], v[34:35], v[222:223]
	v_pk_mul_f32 v[32:33], v[32:33], v[220:221]
	v_pk_mul_f32 v[28:29], v[28:29], v[162:163]
	v_pk_mul_f32 v[24:25], v[24:25], v[166:167]
	v_pk_mul_f32 v[20:21], v[20:21], v[170:171]
	v_pk_mul_f32 v[30:31], v[30:31], v[164:165]
	v_pk_mul_f32 v[26:27], v[26:27], v[168:169]
	v_pk_mul_f32 v[22:23], v[22:23], v[172:173]
	v_pk_mul_f32 v[18:19], v[18:19], v[222:223]
	v_pk_mul_f32 v[16:17], v[16:17], v[220:221]
; __device__ __forceinline__ void partialSM(f32x16& p0, f32x16& p1, float& m_reg, float& mn, float& alpha) {
;     ...
;   if (__builtin_expect(__all(pmax - m_reg <= THR / SCALE), 1)) { mn = m_reg; alpha = 1.f; }
;   else { mn = fmaxf(m_reg, pmax); alpha = __builtin_amdgcn_exp2f((m_reg - mn) * C); m_reg = mn; }
;   float mnC = -mn * C;
; #pragma unroll
;   for (int r = 0; r < 16; ++r) p0[r] = fmaf(p0[r], C, mnC);
; #pragma unroll
;   for (int r = 0; r < 16; ++r) p1[r] = fmaf(p1[r], C, mnC);
; #pragma unroll
;   for (int r = 0; r < 16; ++r) p0[r] = __builtin_amdgcn_exp2f(p0[r]);
.LBB0_448:
	v_cndmask_b32_e64 v220, v161, v160, s[6:7]
	v_mul_f32_e32 v221, 0xbe0293ee, v220
	v_fmamk_f32 v80, v80, 0x3e0293ee, v221
	v_fmamk_f32 v81, v81, 0x3e0293ee, v221
	v_fmamk_f32 v82, v82, 0x3e0293ee, v221
	v_fmamk_f32 v83, v83, 0x3e0293ee, v221
	v_fmamk_f32 v84, v84, 0x3e0293ee, v221
	v_fmamk_f32 v85, v85, 0x3e0293ee, v221
	v_fmamk_f32 v86, v86, 0x3e0293ee, v221
	v_fmamk_f32 v87, v87, 0x3e0293ee, v221
	v_fmamk_f32 v88, v88, 0x3e0293ee, v221
	v_fmamk_f32 v89, v89, 0x3e0293ee, v221
	v_fmamk_f32 v90, v90, 0x3e0293ee, v221
	v_fmamk_f32 v91, v91, 0x3e0293ee, v221
	v_fmamk_f32 v92, v92, 0x3e0293ee, v221
	v_fmamk_f32 v93, v93, 0x3e0293ee, v221
	v_fmamk_f32 v94, v94, 0x3e0293ee, v221
	v_fmamk_f32 v95, v95, 0x3e0293ee, v221
	v_exp_f32_e32 v172, v80
	v_exp_f32_e32 v175, v81
	v_exp_f32_e32 v171, v82
	v_exp_f32_e32 v173, v83
	v_exp_f32_e32 v170, v84
	v_exp_f32_e32 v174, v85
	v_exp_f32_e32 v168, v86
	v_exp_f32_e32 v169, v87
	v_exp_f32_e32 v165, v88
	v_exp_f32_e32 v167, v89
	v_exp_f32_e32 v164, v90
	v_exp_f32_e32 v166, v91
	v_exp_f32_e32 v161, v92
	v_exp_f32_e32 v163, v93
	v_exp_f32_e32 v160, v94
	v_exp_f32_e32 v162, v95
	v_fmamk_f32 v230, v64, 0x3e0293ee, v221
	v_fmamk_f32 v231, v65, 0x3e0293ee, v221
	v_fmamk_f32 v232, v66, 0x3e0293ee, v221
	v_fmamk_f32 v233, v67, 0x3e0293ee, v221
	v_fmamk_f32 v234, v68, 0x3e0293ee, v221
	v_fmamk_f32 v223, v69, 0x3e0293ee, v221
	v_fmamk_f32 v224, v70, 0x3e0293ee, v221
	v_fmamk_f32 v225, v71, 0x3e0293ee, v221
	v_fmamk_f32 v226, v72, 0x3e0293ee, v221
	v_fmamk_f32 v227, v73, 0x3e0293ee, v221
	v_fmamk_f32 v228, v74, 0x3e0293ee, v221
	v_fmamk_f32 v229, v75, 0x3e0293ee, v221
	v_fmamk_f32 v222, v76, 0x3e0293ee, v221
	v_fmamk_f32 v235, v77, 0x3e0293ee, v221
	v_fmamk_f32 v236, v78, 0x3e0293ee, v221
	v_fmac_f32_e32 v221, 0x3e0293ee, v79
	s_waitcnt lgkmcnt(0)
	s_barrier
; __device__ __forceinline__ void finishSM(f32x16& p0, f32x16& p1, float alpha, float& l_reg, bf16x8& pa0, bf16x8& pa1, bf16x8& pa2, bf16x8& pa3) {
; #pragma unroll
;   for (int r = 0; r < 16; ++r) p1[r] = __builtin_amdgcn_exp2f(p1[r]);
;   float ps = 0;
; #pragma unroll
;   for (int r = 0; r < 16; ++r) ps += p0[r];
; #pragma unroll
;   for (int r = 0; r < 16; ++r) ps += p1[r];
;   { auto rr = __builtin_amdgcn_permlane32_swap(__float_as_uint(ps), __float_as_uint(ps), false, false);
;     ps = __uint_as_float(rr[0]) + __uint_as_float(rr[1]); }
;   l_reg = l_reg * alpha + ps;
;     ...
;   PK4(p0, 0, pa0); PK4(p0, 8, pa1); PK4(p1, 0, pa2); PK4(p1, 8, pa3);
;     ...
; }
; __device__ __forceinline__ void qkt(f32x16& p0, f32x16& p1, const bf16_t* Ks, const bf16x8* qr, int r32, int hi) {
;   p0 = f32x16{}; p1 = f32x16{};
; #pragma unroll
;   for (int d0 = 0; d0 < 8; ++d0) { int cb = (d0 * 16 + hi * 8) * 2;
;     bf16x8 b0 = *reinterpret_cast<const bf16x8*>((const char*)Ks + KSWZ(r32, cb));
;     bf16x8 b1 = *reinterpret_cast<const bf16x8*>((const char*)Ks + KSWZ(32 + r32, cb));
;     p0 = __builtin_amdgcn_mfma_f32_32x32x16_bf16(b0, qr[d0], p0, 0, 0, 0);
;     p1 = __builtin_amdgcn_mfma_f32_32x32x16_bf16(b1, qr[d0], p1, 0, 0, 0); }
	ds_read_b128 v[64:67], v204 offset:32768
	ds_read_b128 v[68:71], v204 offset:40960
	ds_read_b128 v[238:241], v205 offset:32768
	ds_read_b128 v[242:245], v205 offset:40960
	ds_read_b128 v[248:251], v206 offset:32768
	ds_read_b128 v[252:255], v206 offset:40960
	v_exp_f32_e32 v230, v230
	v_exp_f32_e32 v231, v231
	s_waitcnt lgkmcnt(5)
	v_mfma_f32_32x32x16_bf16 v[80:95], v[64:67], v[124:127], 0
	v_exp_f32_e32 v232, v232
	v_exp_f32_e32 v233, v233
	v_exp_f32_e32 v234, v234
	v_exp_f32_e32 v223, v223
	v_exp_f32_e32 v224, v224
	v_exp_f32_e32 v225, v225
	v_exp_f32_e32 v226, v226
	s_waitcnt lgkmcnt(4)
	v_mfma_f32_32x32x16_bf16 v[64:79], v[68:71], v[124:127], 0
	v_exp_f32_e32 v227, v227
	v_exp_f32_e32 v228, v228
	v_exp_f32_e32 v229, v229
	v_exp_f32_e32 v237, v222
	v_exp_f32_e32 v235, v235
	v_exp_f32_e32 v236, v236
	s_waitcnt lgkmcnt(3)
	v_mfma_f32_32x32x16_bf16 v[80:95], v[238:241], v[120:123], v[80:95]
	s_waitcnt lgkmcnt(2)
	v_mfma_f32_32x32x16_bf16 v[64:79], v[242:245], v[120:123], v[64:79]
	ds_read_b128 v[238:241], v207 offset:32768
	ds_read_b128 v[242:245], v207 offset:40960
	s_waitcnt lgkmcnt(3)
	v_mfma_f32_32x32x16_bf16 v[80:95], v[248:251], v[116:119], v[80:95]
	s_waitcnt lgkmcnt(2)
	v_mfma_f32_32x32x16_bf16 v[64:79], v[252:255], v[116:119], v[64:79]
	ds_read_b128 v[248:251], v208 offset:32768
	ds_read_b128 v[252:255], v208 offset:40960
	s_waitcnt lgkmcnt(3)
	v_mfma_f32_32x32x16_bf16 v[80:95], v[238:241], v[112:115], v[80:95]
	s_waitcnt lgkmcnt(2)
	v_mfma_f32_32x32x16_bf16 v[64:79], v[242:245], v[112:115], v[64:79]
	ds_read_b128 v[238:241], v209 offset:32768
	ds_read_b128 v[242:245], v209 offset:40960
	s_waitcnt lgkmcnt(3)
	v_mfma_f32_32x32x16_bf16 v[80:95], v[248:251], v[108:111], v[80:95]
	s_waitcnt lgkmcnt(2)
	v_mfma_f32_32x32x16_bf16 v[64:79], v[252:255], v[108:111], v[64:79]
	ds_read_b128 v[248:251], v210 offset:32768
	ds_read_b128 v[252:255], v210 offset:40960
	s_waitcnt lgkmcnt(3)
	v_mfma_f32_32x32x16_bf16 v[80:95], v[238:241], v[104:107], v[80:95]
	s_waitcnt lgkmcnt(2)
	v_mfma_f32_32x32x16_bf16 v[64:79], v[242:245], v[104:107], v[64:79]
	ds_read_b128 v[238:241], v211 offset:32768
	ds_read_b128 v[242:245], v211 offset:40960
	s_waitcnt lgkmcnt(3)
	v_mfma_f32_32x32x16_bf16 v[80:95], v[248:251], v[100:103], v[80:95]
	s_waitcnt lgkmcnt(2)
	v_mfma_f32_32x32x16_bf16 v[64:79], v[252:255], v[100:103], v[64:79]
	s_waitcnt lgkmcnt(1)
	v_mfma_f32_32x32x16_bf16 v[80:95], v[238:241], v[96:99], v[80:95]
	v_exp_f32_e32 v238, v221
	v_add_f32_e32 v221, 0, v172
	v_add_f32_e32 v221, v175, v221
	v_add_f32_e32 v221, v171, v221
	v_add_f32_e32 v221, v173, v221
	v_add_f32_e32 v221, v170, v221
	v_add_f32_e32 v221, v174, v221
	v_add_f32_e32 v221, v168, v221
	v_add_f32_e32 v221, v169, v221
	v_add_f32_e32 v221, v165, v221
	v_add_f32_e32 v221, v167, v221
	v_add_f32_e32 v221, v164, v221
	v_add_f32_e32 v221, v166, v221
	v_add_f32_e32 v221, v161, v221
	v_add_f32_e32 v221, v163, v221
	v_add_f32_e32 v221, v160, v221
	v_add_f32_e32 v221, v162, v221
	v_add_f32_e32 v221, v230, v221
	v_add_f32_e32 v221, v231, v221
	v_add_f32_e32 v221, v232, v221
	v_add_f32_e32 v221, v233, v221
	v_add_f32_e32 v221, v234, v221
	v_add_f32_e32 v221, v223, v221
	v_add_f32_e32 v221, v224, v221
	v_add_f32_e32 v221, v225, v221
	v_add_f32_e32 v221, v226, v221
	v_add_f32_e32 v221, v227, v221
	s_waitcnt lgkmcnt(0)
	v_mfma_f32_32x32x16_bf16 v[64:79], v[242:245], v[96:99], v[64:79]
	v_add_f32_e32 v221, v228, v221
	v_add_f32_e32 v221, v229, v221
	v_add_f32_e32 v221, v237, v221
	v_add_f32_e32 v221, v235, v221
	v_add_f32_e32 v221, v236, v221
	v_add_f32_e32 v221, v238, v221
	v_mov_b32_e32 v222, v221
	v_cvt_pk_bf16_f32 v172, v172, v175
	v_cvt_pk_bf16_f32 v173, v171, v173
	v_cvt_pk_bf16_f32 v174, v170, v174
	v_cvt_pk_bf16_f32 v175, v168, v169
	v_cvt_pk_bf16_f32 v168, v165, v167
	v_cvt_pk_bf16_f32 v169, v164, v166
	v_cvt_pk_bf16_f32 v170, v161, v163
	v_cvt_pk_bf16_f32 v171, v160, v162
	v_cvt_pk_bf16_f32 v164, v230, v231
	v_cvt_pk_bf16_f32 v165, v232, v233
	v_cvt_pk_bf16_f32 v166, v234, v223
	v_cvt_pk_bf16_f32 v167, v224, v225
	v_cvt_pk_bf16_f32 v160, v226, v227
	v_cvt_pk_bf16_f32 v161, v228, v229
	v_cvt_pk_bf16_f32 v162, v237, v235
	v_cvt_pk_bf16_f32 v163, v236, v238
	s_nop 1
	v_permlane32_swap_b32_e32 v221, v222
	v_permlane32_swap_b32_e32 v172, v174
	v_permlane32_swap_b32_e32 v173, v175
	v_permlane32_swap_b32_e32 v168, v170
	v_permlane32_swap_b32_e32 v169, v171
	v_permlane32_swap_b32_e32 v164, v166
	v_permlane32_swap_b32_e32 v165, v167
	v_permlane32_swap_b32_e32 v160, v162
	v_permlane32_swap_b32_e32 v161, v163
	s_cmp_ge_u32 s49, s45
	s_cselect_b64 s[20:21], -1, 0
	s_and_b64 vcc, exec, s[20:21]
	s_cbranch_vccnz .LBB0_450
	v_add_co_u32_e32 v128, vcc, 0x2feb8000, v192
	s_nop 1
	v_addc_co_u32_e32 v129, vcc, 0, v193, vcc
	v_add_co_u32_e32 v132, vcc, 0x2feb8000, v190
	s_nop 1
	v_addc_co_u32_e32 v133, vcc, 0, v191, vcc
	v_add_co_u32_e32 v136, vcc, 0x2f5b8000, v192
	global_load_dwordx4 v[128:131], v[128:129], off
	s_nop 0
	global_load_dwordx4 v[132:135], v[132:133], off
	v_addc_co_u32_e32 v137, vcc, 0, v193, vcc
	v_add_co_u32_e32 v140, vcc, 0x2f5b8000, v190
	s_nop 1
	v_addc_co_u32_e32 v141, vcc, 0, v191, vcc
	global_load_dwordx4 v[136:139], v[136:137], off
	s_nop 0
	global_load_dwordx4 v[140:143], v[140:141], off

; __device__ __forceinline__ void finishSM(f32x16& p0, f32x16& p1, float alpha, float& l_reg, bf16x8& pa0, bf16x8& pa1, bf16x8& pa2, bf16x8& pa3) {
; #pragma unroll
;   for (int r = 0; r < 16; ++r) p1[r] = __builtin_amdgcn_exp2f(p1[r]);
;   float ps = 0;
; #pragma unroll
;   for (int r = 0; r < 16; ++r) ps += p0[r];
; #pragma unroll
;   for (int r = 0; r < 16; ++r) ps += p1[r];
;   { auto rr = __builtin_amdgcn_permlane32_swap(__float_as_uint(ps), __float_as_uint(ps), false, false);
;     ps = __uint_as_float(rr[0]) + __uint_as_float(rr[1]); }
;   l_reg = l_reg * alpha + ps;
;     ...
;   PK4(p0, 0, pa0); PK4(p0, 8, pa1); PK4(p1, 0, pa2); PK4(p1, 8, pa3);
;     ...
; }
; __device__ __forceinline__ void qkt(f32x16& p0, f32x16& p1, const bf16_t* Ks, const bf16x8* qr, int r32, int hi) {
;   p0 = f32x16{}; p1 = f32x16{};
; #pragma unroll
;   for (int d0 = 0; d0 < 8; ++d0) { int cb = (d0 * 16 + hi * 8) * 2;
;     bf16x8 b0 = *reinterpret_cast<const bf16x8*>((const char*)Ks + KSWZ(r32, cb));
;     bf16x8 b1 = *reinterpret_cast<const bf16x8*>((const char*)Ks + KSWZ(32 + r32, cb));
;     p0 = __builtin_amdgcn_mfma_f32_32x32x16_bf16(b0, qr[d0], p0, 0, 0, 0);
;     p1 = __builtin_amdgcn_mfma_f32_32x32x16_bf16(b1, qr[d0], p1, 0, 0, 0); }
.LBB0_1524:
	ds_read_b128 v[64:67], v204 offset:49152
	ds_read_b128 v[68:71], v204 offset:57344
	ds_read_b128 v[218:221], v205 offset:49152
	ds_read_b128 v[222:225], v205 offset:57344
	ds_read_b128 v[248:251], v206 offset:49152
	ds_read_b128 v[252:255], v206 offset:57344
	v_add_f32_e32 v161, 0, v175
	v_add_f32_e32 v161, v191, v161
	s_waitcnt lgkmcnt(5)
	v_mfma_f32_32x32x16_bf16 v[80:95], v[64:67], v[124:127], 0
	v_add_f32_e32 v161, v173, v161
	v_add_f32_e32 v161, v190, v161
	v_add_f32_e32 v161, v172, v161
	v_add_f32_e32 v161, v174, v161
	v_add_f32_e32 v161, v170, v161
	v_add_f32_e32 v161, v171, v161
	v_add_f32_e32 v161, v167, v161
	s_waitcnt lgkmcnt(4)
	v_mfma_f32_32x32x16_bf16 v[64:79], v[68:71], v[124:127], 0
	v_add_f32_e32 v161, v169, v161
	v_add_f32_e32 v161, v166, v161
	v_add_f32_e32 v161, v168, v161
	v_exp_f32_e32 v156, v156
	v_add_f32_e32 v161, v163, v161
	v_exp_f32_e32 v157, v157
	v_add_f32_e32 v161, v164, v161
	s_waitcnt lgkmcnt(3)
	v_mfma_f32_32x32x16_bf16 v[80:95], v[218:221], v[120:123], v[80:95]
	v_exp_f32_e32 v154, v154
	v_add_f32_e32 v161, v162, v161
	v_exp_f32_e32 v155, v155
	v_add_f32_e32 v161, v165, v161
	v_exp_f32_e32 v150, v150
	v_add_f32_e32 v161, v156, v161
	v_exp_f32_e32 v151, v151
	s_waitcnt lgkmcnt(2)
	v_mfma_f32_32x32x16_bf16 v[64:79], v[222:225], v[120:123], v[64:79]
	ds_read_b128 v[218:221], v207 offset:49152
	ds_read_b128 v[222:225], v207 offset:57344
	v_add_f32_e32 v161, v157, v161
	v_exp_f32_e32 v148, v148
	v_add_f32_e32 v161, v154, v161
	v_exp_f32_e32 v149, v149
	v_add_f32_e32 v161, v155, v161
	v_exp_f32_e32 v144, v144
	s_waitcnt lgkmcnt(3)
	v_mfma_f32_32x32x16_bf16 v[80:95], v[248:251], v[116:119], v[80:95]
	v_add_f32_e32 v161, v150, v161
	v_exp_f32_e32 v145, v145
	v_add_f32_e32 v161, v151, v161
	v_exp_f32_e32 v158, v158
	v_add_f32_e32 v161, v148, v161
	v_exp_f32_e32 v159, v159
	v_add_f32_e32 v161, v149, v161
	s_waitcnt lgkmcnt(2)
	v_mfma_f32_32x32x16_bf16 v[64:79], v[252:255], v[116:119], v[64:79]
	ds_read_b128 v[248:251], v208 offset:49152
	ds_read_b128 v[252:255], v208 offset:57344
	v_exp_f32_e32 v152, v152
	v_add_f32_e32 v161, v144, v161
	v_exp_f32_e32 v153, v153
	v_add_f32_e32 v161, v145, v161
	v_exp_f32_e32 v146, v146
	v_add_f32_e32 v161, v158, v161
	s_waitcnt lgkmcnt(3)
	v_mfma_f32_32x32x16_bf16 v[80:95], v[218:221], v[112:115], v[80:95]
	v_exp_f32_e32 v147, v147
	v_add_f32_e32 v161, v159, v161
	v_add_f32_e32 v161, v152, v161
	v_add_f32_e32 v161, v153, v161
	v_add_f32_e32 v161, v146, v161
	v_add_f32_e32 v215, v147, v161
	s_waitcnt lgkmcnt(2)
	v_mfma_f32_32x32x16_bf16 v[64:79], v[222:225], v[112:115], v[64:79]
	ds_read_b128 v[218:221], v209 offset:49152
	ds_read_b128 v[222:225], v209 offset:57344
	s_waitcnt lgkmcnt(3)
	v_mfma_f32_32x32x16_bf16 v[80:95], v[248:251], v[108:111], v[80:95]
	s_waitcnt lgkmcnt(2)
	v_mfma_f32_32x32x16_bf16 v[64:79], v[252:255], v[108:111], v[64:79]
	ds_read_b128 v[248:251], v210 offset:49152
	ds_read_b128 v[252:255], v210 offset:57344
	s_waitcnt lgkmcnt(3)
	v_mfma_f32_32x32x16_bf16 v[80:95], v[218:221], v[104:107], v[80:95]
	s_waitcnt lgkmcnt(2)
	v_mfma_f32_32x32x16_bf16 v[64:79], v[222:225], v[104:107], v[64:79]
	ds_read_b128 v[218:221], v211 offset:49152
	ds_read_b128 v[222:225], v211 offset:57344
	s_waitcnt lgkmcnt(3)
	v_mfma_f32_32x32x16_bf16 v[80:95], v[248:251], v[100:103], v[80:95]
	s_waitcnt lgkmcnt(2)
	v_mfma_f32_32x32x16_bf16 v[64:79], v[252:255], v[100:103], v[64:79]
	s_waitcnt lgkmcnt(1)
	v_mfma_f32_32x32x16_bf16 v[80:95], v[218:221], v[96:99], v[80:95]
	v_mov_b32_e32 v218, v215
	s_nop 1
	v_permlane32_swap_b32_e32 v215, v218
	v_cvt_pk_bf16_f32 v220, v175, v191
	v_cvt_pk_bf16_f32 v221, v173, v190
	s_waitcnt lgkmcnt(0)
	v_mfma_f32_32x32x16_bf16 v[64:79], v[222:225], v[96:99], v[64:79]
	v_cvt_pk_bf16_f32 v222, v172, v174
	v_cvt_pk_bf16_f32 v223, v170, v171
	v_cvt_pk_bf16_f32 v170, v167, v169
	v_cvt_pk_bf16_f32 v171, v166, v168
	v_cvt_pk_bf16_f32 v172, v163, v164
	v_cvt_pk_bf16_f32 v173, v162, v165
	v_cvt_pk_bf16_f32 v162, v156, v157
	v_cvt_pk_bf16_f32 v163, v154, v155
	v_cvt_pk_bf16_f32 v164, v150, v151
	v_cvt_pk_bf16_f32 v165, v148, v149
	v_cvt_pk_bf16_f32 v166, v144, v145
	v_cvt_pk_bf16_f32 v167, v158, v159
	v_cvt_pk_bf16_f32 v168, v152, v153
	v_cvt_pk_bf16_f32 v169, v146, v147
	s_nop 0
	v_permlane32_swap_b32_e32 v220, v222
	v_permlane32_swap_b32_e32 v221, v223
	v_permlane32_swap_b32_e32 v170, v172
	v_permlane32_swap_b32_e32 v171, v173
	v_permlane32_swap_b32_e32 v162, v164
	v_permlane32_swap_b32_e32 v163, v165
	v_permlane32_swap_b32_e32 v166, v168
	v_permlane32_swap_b32_e32 v167, v169
	v_lshl_add_u64 v[192:193], s[18:19], 0, v[180:181]
	v_add_co_u32_e32 v144, vcc, s63, v192
	v_lshl_add_u64 v[190:191], s[18:19], 0, v[182:183]
	s_nop 0
	v_addc_co_u32_e32 v145, vcc, 0, v193, vcc
	v_add_co_u32_e32 v148, vcc, s63, v190
	s_nop 1
	v_addc_co_u32_e32 v149, vcc, 0, v191, vcc
	v_add_co_u32_e32 v152, vcc, s64, v192
	global_load_dwordx4 v[144:147], v[144:145], off
	s_nop 0
	global_load_dwordx4 v[148:151], v[148:149], off
	v_addc_co_u32_e32 v153, vcc, 0, v193, vcc
	v_add_co_u32_e32 v156, vcc, s64, v190
	s_nop 1
	v_addc_co_u32_e32 v157, vcc, 0, v191, vcc
	global_load_dwordx4 v[152:155], v[152:153], off
	s_nop 0
	global_load_dwordx4 v[156:159], v[156:157], off
	ds_read_b64_tr_b16 v[224:225], v196 offset:0
	ds_read_b64_tr_b16 v[226:227], v196 offset:0x800
	ds_read_b64_tr_b16 v[228:229], v196 offset:0x1000
	ds_read_b64_tr_b16 v[230:231], v196 offset:0x1800
	ds_read_b64_tr_b16 v[232:233], v196 offset:0x200
	ds_read_b64_tr_b16 v[234:235], v196 offset:0xa00
	ds_read_b64_tr_b16 v[236:237], v196 offset:0x1200
	ds_read_b64_tr_b16 v[238:239], v196 offset:0x1a00
	s_waitcnt lgkmcnt(0)
; __device__ __forceinline__ void partialSM(f32x16& p0, f32x16& p1, float& m_reg, float& mn, float& alpha) {
;   constexpr float C = SCALE * 1.4426950408889634f;
;   float pmax = p0[0];
; #pragma unroll
;   for (int r = 1; r < 16; ++r) pmax = fmaxf(pmax, p0[r]);
; #pragma unroll
;   for (int r = 0; r < 16; ++r) pmax = fmaxf(pmax, p1[r]);
;   { auto rr = __builtin_amdgcn_permlane32_swap(__float_as_uint(pmax), __float_as_uint(pmax), false, false);
;     pmax = fmaxf(__uint_as_float(rr[0]), __uint_as_float(rr[1])); }
; template <int DA, int DB> __device__ __forceinline__ void pv_pair(f32x16& oa, f32x16& ob, int vb, bf16x8 pa0, bf16x8 pa1, bf16x8 pa2, bf16x8 pa3) {
;     ...
;   { const s16x4 al0 = tr_read<v_rd_off(DA, 0, 0)>(vb), ah0 = tr_read<v_rd_off(DA, 0, 1)>(vb), al1 = tr_read<v_rd_off(DA, 1, 0)>(vb), ah1 = tr_read<v_rd_off(DA, 1, 1)>(vb);
;     const s16x4 bl0 = tr_read<v_rd_off(DB, 0, 0)>(vb), bh0 = tr_read<v_rd_off(DB, 0, 1)>(vb), bl1 = tr_read<v_rd_off(DB, 1, 0)>(vb), bh1 = tr_read<v_rd_off(DB, 1, 1)>(vb);
;     asm volatile("s_waitcnt lgkmcnt(0)" ::: "memory"); SBAR();
;     oa = __builtin_amdgcn_mfma_f32_32x32x16_bf16(pa0, PK(al0, ah0), oa, 0, 0, 0); ob = __builtin_amdgcn_mfma_f32_32x32x16_bf16(pa0, PK(bl0, bh0), ob, 0, 0, 0);
;     oa = __builtin_amdgcn_mfma_f32_32x32x16_bf16(pa1, PK(al1, ah1), oa, 0, 0, 0); ob = __builtin_amdgcn_mfma_f32_32x32x16_bf16(pa1, PK(bl1, bh1), ob, 0, 0, 0); }
;   { const s16x4 al2 = tr_read<v_rd_off(DA, 2, 0)>(vb), ah2 = tr_read<v_rd_off(DA, 2, 1)>(vb), al3 = tr_read<v_rd_off(DA, 3, 0)>(vb), ah3 = tr_read<v_rd_off(DA, 3, 1)>(vb);
;     const s16x4 bl2 = tr_read<v_rd_off(DB, 2, 0)>(vb), bh2 = tr_read<v_rd_off(DB, 2, 1)>(vb), bl3 = tr_read<v_rd_off(DB, 3, 0)>(vb), bh3 = tr_read<v_rd_off(DB, 3, 1)>(vb);
;     asm volatile("s_waitcnt lgkmcnt(0)" ::: "memory"); SBAR();
;     oa = __builtin_amdgcn_mfma_f32_32x32x16_bf16(pa2, PK(al2, ah2), oa, 0, 0, 0); ob = __builtin_amdgcn_mfma_f32_32x32x16_bf16(pa2, PK(bl2, bh2), ob, 0, 0, 0);
;     oa = __builtin_amdgcn_mfma_f32_32x32x16_bf16(pa3, PK(al3, ah3), oa, 0, 0, 0); ob = __builtin_amdgcn_mfma_f32_32x32x16_bf16(pa3, PK(bl3, bh3), ob, 0, 0, 0); }
;     ...
; }
; __device__ __forceinline__ void pv_d0(f32x16* o, int vb, bf16x8 pa0, bf16x8 pa1, bf16x8 pa2, bf16x8 pa3) {
;   pv_pair<0, 1>(o[0], o[1], vb, pa0, pa1, pa2, pa3); pv_pair<2, 3>(o[2], o[3], vb, pa0, pa1, pa2, pa3);
	s_nop 0
	v_mfma_f32_32x32x16_bf16 v[0:15], v[220:223], v[224:227], v[0:15]
	ds_read_b64_tr_b16 v[224:225], v196 offset:0x2000
	ds_read_b64_tr_b16 v[226:227], v196 offset:0x2800
	v_mfma_f32_32x32x16_bf16 v[48:63], v[220:223], v[232:235], v[48:63]
	v_mfma_f32_32x32x16_bf16 v[0:15], v[170:173], v[228:231], v[0:15]
	ds_read_b64_tr_b16 v[228:229], v196 offset:0x3000
	ds_read_b64_tr_b16 v[230:231], v196 offset:0x3800
	ds_read_b64_tr_b16 v[232:233], v196 offset:0x2200
	ds_read_b64_tr_b16 v[234:235], v196 offset:0x2a00
	ds_read_b64_tr_b16 v[240:241], v196 offset:0x3200
	ds_read_b64_tr_b16 v[242:243], v196 offset:0x3a00
	s_waitcnt lgkmcnt(0)
	v_mfma_f32_32x32x16_bf16 v[48:63], v[170:173], v[236:239], v[48:63]
	v_mfma_f32_32x32x16_bf16 v[0:15], v[162:165], v[224:227], v[0:15]
	ds_read_b64_tr_b16 v[224:225], v196 offset:0x400
	ds_read_b64_tr_b16 v[226:227], v196 offset:0xc00
	v_mfma_f32_32x32x16_bf16 v[48:63], v[162:165], v[232:235], v[48:63]
	v_mfma_f32_32x32x16_bf16 v[0:15], v[166:169], v[228:231], v[0:15]
	ds_read_b64_tr_b16 v[228:229], v196 offset:0x1400
	ds_read_b64_tr_b16 v[230:231], v196 offset:0x1c00
	ds_read_b64_tr_b16 v[232:233], v196 offset:0x600
	ds_read_b64_tr_b16 v[234:235], v196 offset:0xe00
	ds_read_b64_tr_b16 v[236:237], v196 offset:0x1600
	ds_read_b64_tr_b16 v[238:239], v196 offset:0x1e00
	s_waitcnt lgkmcnt(0)
	v_mfma_f32_32x32x16_bf16 v[48:63], v[166:169], v[240:243], v[48:63]
	v_mfma_f32_32x32x16_bf16 v[32:47], v[220:223], v[224:227], v[32:47]
	v_mfma_f32_32x32x16_bf16 v[16:31], v[220:223], v[232:235], v[16:31]
	ds_read_b64_tr_b16 v[220:221], v196 offset:0x2400
	ds_read_b64_tr_b16 v[222:223], v196 offset:0x2c00
	ds_read_b64_tr_b16 v[224:225], v196 offset:0x3400
	ds_read_b64_tr_b16 v[226:227], v196 offset:0x3c00
	v_mfma_f32_32x32x16_bf16 v[32:47], v[170:173], v[228:231], v[32:47]
	ds_read_b64_tr_b16 v[228:229], v196 offset:0x2600
	ds_read_b64_tr_b16 v[230:231], v196 offset:0x2e00
	ds_read_b64_tr_b16 v[232:233], v196 offset:0x3600
	ds_read_b64_tr_b16 v[234:235], v196 offset:0x3e00
	s_waitcnt lgkmcnt(0)
	v_mfma_f32_32x32x16_bf16 v[16:31], v[170:173], v[236:239], v[16:31]
	v_max_f32_e32 v161, v81, v81
	v_max_f32_e32 v170, v80, v80
	v_max_f32_e32 v161, v170, v161
	v_max3_f32 v161, v161, v82, v83
	v_max3_f32 v161, v161, v84, v85
	v_max3_f32 v161, v161, v86, v87
	v_max3_f32 v161, v161, v88, v89
	v_max3_f32 v161, v161, v90, v91
	v_max3_f32 v161, v161, v92, v93
	v_max3_f32 v161, v161, v94, v95
	v_max3_f32 v161, v161, v64, v65
	v_max3_f32 v161, v161, v66, v67
	v_max3_f32 v161, v161, v68, v69
	v_max3_f32 v161, v161, v70, v71
	v_max3_f32 v161, v161, v72, v73
	v_mfma_f32_32x32x16_bf16 v[32:47], v[162:165], v[220:223], v[32:47]
	v_max3_f32 v161, v161, v74, v75
	v_max3_f32 v161, v161, v76, v77
	v_max3_f32 v161, v161, v78, v79
	s_barrier
	s_waitcnt vmcnt(4)
	v_mfma_f32_32x32x16_bf16 v[16:31], v[162:165], v[228:231], v[16:31]
	v_mov_b32_e32 v162, v161
	s_nop 1
	v_permlane32_swap_b32_e32 v161, v162
	v_max_f32_e32 v162, v162, v162
	v_max_f32_e32 v161, v161, v161
	v_max_f32_e32 v161, v161, v162
	v_max_f32_e32 v163, v160, v160
	v_sub_f32_e32 v162, v161, v160
	v_max_f32_e32 v161, v163, v161
	v_mfma_f32_32x32x16_bf16 v[32:47], v[166:169], v[224:227], v[32:47]
	v_sub_f32_e32 v163, v160, v161
	v_mul_f32_e32 v163, 0x3e0293ee, v163
	v_exp_f32_e32 v163, v163
	v_cmp_ge_f32_e32 vcc, s62, v162
	s_cmp_eq_u64 vcc, exec
	s_cselect_b64 s[6:7], -1, 0
	v_cndmask_b32_e64 v219, v163, 1.0, s[6:7]
	v_mfma_f32_32x32x16_bf16 v[16:31], v[166:169], v[232:235], v[16:31]
	v_cmp_gt_f32_e32 vcc, 1.0, v219
	s_waitcnt vmcnt(4)
	ds_write_b128 v200, v[128:131]
	ds_write_b128 v201, v[132:135]
	ds_write_b128 v202, v[136:139] offset:32768
	ds_write_b128 v203, v[140:143] offset:32768
	s_cbranch_vccz .LBB0_1528
	s_and_saveexec_b64 s[20:21], s[4:5]
	ds_write_b32 v198, v219 offset:128
	s_or_b64 exec, exec, s[20:21]
	s_waitcnt lgkmcnt(0)
	v_add_u32_e32 v174, v195, v197
	ds_read_b128 v[162:165], v174 offset:224
	ds_read_b128 v[166:169], v174 offset:192
	ds_read_b128 v[170:173], v174 offset:160
	ds_read_b128 v[220:223], v174 offset:128
	s_waitcnt lgkmcnt(3)
	v_pk_mul_f32 v[12:13], v[12:13], v[162:163]
	s_waitcnt lgkmcnt(2)
	v_pk_mul_f32 v[8:9], v[8:9], v[166:167]
	s_waitcnt lgkmcnt(1)
	v_pk_mul_f32 v[4:5], v[4:5], v[170:171]
	v_pk_mul_f32 v[14:15], v[14:15], v[164:165]
	v_pk_mul_f32 v[10:11], v[10:11], v[168:169]
	v_pk_mul_f32 v[6:7], v[6:7], v[172:173]
	s_waitcnt lgkmcnt(0)
	v_pk_mul_f32 v[2:3], v[2:3], v[222:223]
	v_pk_mul_f32 v[0:1], v[0:1], v[220:221]
	v_pk_mul_f32 v[60:61], v[60:61], v[162:163]
	v_pk_mul_f32 v[56:57], v[56:57], v[166:167]
	v_pk_mul_f32 v[52:53], v[52:53], v[170:171]
	v_pk_mul_f32 v[62:63], v[62:63], v[164:165]
	v_pk_mul_f32 v[58:59], v[58:59], v[168:169]
	v_pk_mul_f32 v[54:55], v[54:55], v[172:173]
	v_pk_mul_f32 v[50:51], v[50:51], v[222:223]
	v_pk_mul_f32 v[48:49], v[48:49], v[220:221]
	v_pk_mul_f32 v[44:45], v[44:45], v[162:163]
	v_pk_mul_f32 v[40:41], v[40:41], v[166:167]
	v_pk_mul_f32 v[36:37], v[36:37], v[170:171]
	v_pk_mul_f32 v[46:47], v[46:47], v[164:165]
	v_pk_mul_f32 v[42:43], v[42:43], v[168:169]
	v_pk_mul_f32 v[38:39], v[38:39], v[172:173]
	v_pk_mul_f32 v[34:35], v[34:35], v[222:223]
	v_pk_mul_f32 v[32:33], v[32:33], v[220:221]
	v_pk_mul_f32 v[28:29], v[28:29], v[162:163]
	v_pk_mul_f32 v[24:25], v[24:25], v[166:167]
	v_pk_mul_f32 v[20:21], v[20:21], v[170:171]
	v_pk_mul_f32 v[30:31], v[30:31], v[164:165]
	v_pk_mul_f32 v[26:27], v[26:27], v[168:169]
	v_pk_mul_f32 v[22:23], v[22:23], v[172:173]
	v_pk_mul_f32 v[18:19], v[18:19], v[222:223]
	v_pk_mul_f32 v[16:17], v[16:17], v[220:221]
; __device__ __forceinline__ void partialSM(f32x16& p0, f32x16& p1, float& m_reg, float& mn, float& alpha) {
;     ...
;   if (__builtin_expect(__all(pmax - m_reg <= THR / SCALE), 1)) { mn = m_reg; alpha = 1.f; }
;   else { mn = fmaxf(m_reg, pmax); alpha = __builtin_amdgcn_exp2f((m_reg - mn) * C); m_reg = mn; }
;   float mnC = -mn * C;
; #pragma unroll
;   for (int r = 0; r < 16; ++r) p0[r] = fmaf(p0[r], C, mnC);
; #pragma unroll
;   for (int r = 0; r < 16; ++r) p1[r] = fmaf(p1[r], C, mnC);
; #pragma unroll
;   for (int r = 0; r < 16; ++r) p0[r] = __builtin_amdgcn_exp2f(p0[r]);
.LBB0_1528:
	v_cndmask_b32_e64 v220, v161, v160, s[6:7]
	v_mul_f32_e32 v221, 0xbe0293ee, v220
	v_fmamk_f32 v80, v80, 0x3e0293ee, v221
	v_fmamk_f32 v81, v81, 0x3e0293ee, v221
	v_fmamk_f32 v82, v82, 0x3e0293ee, v221
	v_fmamk_f32 v83, v83, 0x3e0293ee, v221
	v_fmamk_f32 v84, v84, 0x3e0293ee, v221
	v_fmamk_f32 v85, v85, 0x3e0293ee, v221
	v_fmamk_f32 v86, v86, 0x3e0293ee, v221
	v_fmamk_f32 v87, v87, 0x3e0293ee, v221
	v_fmamk_f32 v88, v88, 0x3e0293ee, v221
	v_fmamk_f32 v89, v89, 0x3e0293ee, v221
	v_fmamk_f32 v90, v90, 0x3e0293ee, v221
	v_fmamk_f32 v91, v91, 0x3e0293ee, v221
	v_fmamk_f32 v92, v92, 0x3e0293ee, v221
	v_fmamk_f32 v93, v93, 0x3e0293ee, v221
	v_fmamk_f32 v94, v94, 0x3e0293ee, v221
	v_fmamk_f32 v95, v95, 0x3e0293ee, v221
	v_exp_f32_e32 v172, v80
	v_exp_f32_e32 v175, v81
	v_exp_f32_e32 v171, v82
	v_exp_f32_e32 v173, v83
	v_exp_f32_e32 v170, v84
	v_exp_f32_e32 v174, v85
	v_exp_f32_e32 v168, v86
	v_exp_f32_e32 v169, v87
	v_exp_f32_e32 v165, v88
	v_exp_f32_e32 v167, v89
	v_exp_f32_e32 v164, v90
	v_exp_f32_e32 v166, v91
	v_exp_f32_e32 v161, v92
	v_exp_f32_e32 v163, v93
	v_exp_f32_e32 v160, v94
	v_exp_f32_e32 v162, v95
	v_fmamk_f32 v230, v64, 0x3e0293ee, v221
	v_fmamk_f32 v231, v65, 0x3e0293ee, v221
	v_fmamk_f32 v232, v66, 0x3e0293ee, v221
	v_fmamk_f32 v233, v67, 0x3e0293ee, v221
	v_fmamk_f32 v234, v68, 0x3e0293ee, v221
	v_fmamk_f32 v223, v69, 0x3e0293ee, v221
	v_fmamk_f32 v224, v70, 0x3e0293ee, v221
	v_fmamk_f32 v225, v71, 0x3e0293ee, v221
	v_fmamk_f32 v226, v72, 0x3e0293ee, v221
	v_fmamk_f32 v227, v73, 0x3e0293ee, v221
	v_fmamk_f32 v228, v74, 0x3e0293ee, v221
	v_fmamk_f32 v229, v75, 0x3e0293ee, v221
	v_fmamk_f32 v222, v76, 0x3e0293ee, v221
	v_fmamk_f32 v235, v77, 0x3e0293ee, v221
	v_fmamk_f32 v236, v78, 0x3e0293ee, v221
	v_fmac_f32_e32 v221, 0x3e0293ee, v79
	s_waitcnt lgkmcnt(0)
	s_barrier
; __device__ __forceinline__ void finishSM(f32x16& p0, f32x16& p1, float alpha, float& l_reg, bf16x8& pa0, bf16x8& pa1, bf16x8& pa2, bf16x8& pa3) {
; #pragma unroll
;   for (int r = 0; r < 16; ++r) p1[r] = __builtin_amdgcn_exp2f(p1[r]);
;   float ps = 0;
; #pragma unroll
;   for (int r = 0; r < 16; ++r) ps += p0[r];
; #pragma unroll
;   for (int r = 0; r < 16; ++r) ps += p1[r];
;   { auto rr = __builtin_amdgcn_permlane32_swap(__float_as_uint(ps), __float_as_uint(ps), false, false);
;     ps = __uint_as_float(rr[0]) + __uint_as_float(rr[1]); }
;   l_reg = l_reg * alpha + ps;
;     ...
;   PK4(p0, 0, pa0); PK4(p0, 8, pa1); PK4(p1, 0, pa2); PK4(p1, 8, pa3);
;     ...
; }
; __device__ __forceinline__ void qkt(f32x16& p0, f32x16& p1, const bf16_t* Ks, const bf16x8* qr, int r32, int hi) {
;   p0 = f32x16{}; p1 = f32x16{};
; #pragma unroll
;   for (int d0 = 0; d0 < 8; ++d0) { int cb = (d0 * 16 + hi * 8) * 2;
;     bf16x8 b0 = *reinterpret_cast<const bf16x8*>((const char*)Ks + KSWZ(r32, cb));
;     bf16x8 b1 = *reinterpret_cast<const bf16x8*>((const char*)Ks + KSWZ(32 + r32, cb));
;     p0 = __builtin_amdgcn_mfma_f32_32x32x16_bf16(b0, qr[d0], p0, 0, 0, 0);
;     p1 = __builtin_amdgcn_mfma_f32_32x32x16_bf16(b1, qr[d0], p1, 0, 0, 0); }
	ds_read_b128 v[64:67], v204 offset:32768
	ds_read_b128 v[68:71], v204 offset:40960
	ds_read_b128 v[238:241], v205 offset:32768
	ds_read_b128 v[242:245], v205 offset:40960
	ds_read_b128 v[248:251], v206 offset:32768
	ds_read_b128 v[252:255], v206 offset:40960
	v_exp_f32_e32 v230, v230
	v_exp_f32_e32 v231, v231
	s_waitcnt lgkmcnt(5)
	v_mfma_f32_32x32x16_bf16 v[80:95], v[64:67], v[124:127], 0
	v_exp_f32_e32 v232, v232
	v_exp_f32_e32 v233, v233
	v_exp_f32_e32 v234, v234
	v_exp_f32_e32 v223, v223
	v_exp_f32_e32 v224, v224
	v_exp_f32_e32 v225, v225
	v_exp_f32_e32 v226, v226
	s_waitcnt lgkmcnt(4)
	v_mfma_f32_32x32x16_bf16 v[64:79], v[68:71], v[124:127], 0
	v_exp_f32_e32 v227, v227
	v_exp_f32_e32 v228, v228
	v_exp_f32_e32 v229, v229
	v_exp_f32_e32 v237, v222
	v_exp_f32_e32 v235, v235
	v_exp_f32_e32 v236, v236
	s_waitcnt lgkmcnt(3)
	v_mfma_f32_32x32x16_bf16 v[80:95], v[238:241], v[120:123], v[80:95]
	s_waitcnt lgkmcnt(2)
	v_mfma_f32_32x32x16_bf16 v[64:79], v[242:245], v[120:123], v[64:79]
	ds_read_b128 v[238:241], v207 offset:32768
	ds_read_b128 v[242:245], v207 offset:40960
	s_waitcnt lgkmcnt(3)
	v_mfma_f32_32x32x16_bf16 v[80:95], v[248:251], v[116:119], v[80:95]
	s_waitcnt lgkmcnt(2)
	v_mfma_f32_32x32x16_bf16 v[64:79], v[252:255], v[116:119], v[64:79]
	ds_read_b128 v[248:251], v208 offset:32768
	ds_read_b128 v[252:255], v208 offset:40960
	s_waitcnt lgkmcnt(3)
	v_mfma_f32_32x32x16_bf16 v[80:95], v[238:241], v[112:115], v[80:95]
	s_waitcnt lgkmcnt(2)
	v_mfma_f32_32x32x16_bf16 v[64:79], v[242:245], v[112:115], v[64:79]
	ds_read_b128 v[238:241], v209 offset:32768
	ds_read_b128 v[242:245], v209 offset:40960
	s_waitcnt lgkmcnt(3)
	v_mfma_f32_32x32x16_bf16 v[80:95], v[248:251], v[108:111], v[80:95]
	s_waitcnt lgkmcnt(2)
	v_mfma_f32_32x32x16_bf16 v[64:79], v[252:255], v[108:111], v[64:79]
	ds_read_b128 v[248:251], v210 offset:32768
	ds_read_b128 v[252:255], v210 offset:40960
	s_waitcnt lgkmcnt(3)
	v_mfma_f32_32x32x16_bf16 v[80:95], v[238:241], v[104:107], v[80:95]
	s_waitcnt lgkmcnt(2)
	v_mfma_f32_32x32x16_bf16 v[64:79], v[242:245], v[104:107], v[64:79]
	ds_read_b128 v[238:241], v211 offset:32768
	ds_read_b128 v[242:245], v211 offset:40960
	s_waitcnt lgkmcnt(3)
	v_mfma_f32_32x32x16_bf16 v[80:95], v[248:251], v[100:103], v[80:95]
	s_waitcnt lgkmcnt(2)
	v_mfma_f32_32x32x16_bf16 v[64:79], v[252:255], v[100:103], v[64:79]
	s_waitcnt lgkmcnt(1)
	v_mfma_f32_32x32x16_bf16 v[80:95], v[238:241], v[96:99], v[80:95]
	v_exp_f32_e32 v238, v221
	v_add_f32_e32 v221, 0, v172
	v_add_f32_e32 v221, v175, v221
	v_add_f32_e32 v221, v171, v221
	v_add_f32_e32 v221, v173, v221
	v_add_f32_e32 v221, v170, v221
	v_add_f32_e32 v221, v174, v221
	v_add_f32_e32 v221, v168, v221
	v_add_f32_e32 v221, v169, v221
	v_add_f32_e32 v221, v165, v221
	v_add_f32_e32 v221, v167, v221
	v_add_f32_e32 v221, v164, v221
	v_add_f32_e32 v221, v166, v221
	v_add_f32_e32 v221, v161, v221
	v_add_f32_e32 v221, v163, v221
	v_add_f32_e32 v221, v160, v221
	v_add_f32_e32 v221, v162, v221
	v_add_f32_e32 v221, v230, v221
	v_add_f32_e32 v221, v231, v221
	v_add_f32_e32 v221, v232, v221
	v_add_f32_e32 v221, v233, v221
	v_add_f32_e32 v221, v234, v221
	v_add_f32_e32 v221, v223, v221
	v_add_f32_e32 v221, v224, v221
	v_add_f32_e32 v221, v225, v221
	v_add_f32_e32 v221, v226, v221
	v_add_f32_e32 v221, v227, v221
	s_waitcnt lgkmcnt(0)
	v_mfma_f32_32x32x16_bf16 v[64:79], v[242:245], v[96:99], v[64:79]
	v_add_f32_e32 v221, v228, v221
	v_add_f32_e32 v221, v229, v221
	v_add_f32_e32 v221, v237, v221
	v_add_f32_e32 v221, v235, v221
	v_add_f32_e32 v221, v236, v221
	v_add_f32_e32 v221, v238, v221
	v_mov_b32_e32 v222, v221
	v_cvt_pk_bf16_f32 v172, v172, v175
	v_cvt_pk_bf16_f32 v173, v171, v173
	v_cvt_pk_bf16_f32 v174, v170, v174
	v_cvt_pk_bf16_f32 v175, v168, v169
	v_cvt_pk_bf16_f32 v168, v165, v167
	v_cvt_pk_bf16_f32 v169, v164, v166
	v_cvt_pk_bf16_f32 v170, v161, v163
	v_cvt_pk_bf16_f32 v171, v160, v162
	v_cvt_pk_bf16_f32 v164, v230, v231
	v_cvt_pk_bf16_f32 v165, v232, v233
	v_cvt_pk_bf16_f32 v166, v234, v223
	v_cvt_pk_bf16_f32 v167, v224, v225
	v_cvt_pk_bf16_f32 v160, v226, v227
	v_cvt_pk_bf16_f32 v161, v228, v229
	v_cvt_pk_bf16_f32 v162, v237, v235
	v_cvt_pk_bf16_f32 v163, v236, v238
	s_nop 1
	v_permlane32_swap_b32_e32 v221, v222
	v_permlane32_swap_b32_e32 v172, v174
	v_permlane32_swap_b32_e32 v173, v175
	v_permlane32_swap_b32_e32 v168, v170
	v_permlane32_swap_b32_e32 v169, v171
	v_permlane32_swap_b32_e32 v164, v166
	v_permlane32_swap_b32_e32 v165, v167
	v_permlane32_swap_b32_e32 v160, v162
	v_permlane32_swap_b32_e32 v161, v163
	s_cmp_gt_u32 s45, 32
	s_cselect_b64 s[20:21], -1, 0
	s_and_b64 vcc, exec, s[20:21]
	s_cbranch_vccnz .LBB0_1530
	v_add_co_u32_e32 v128, vcc, 0x2feb8000, v192
	s_nop 1
	v_addc_co_u32_e32 v129, vcc, 0, v193, vcc
	v_add_co_u32_e32 v132, vcc, 0x2feb8000, v190
	s_nop 1
	v_addc_co_u32_e32 v133, vcc, 0, v191, vcc
	v_add_co_u32_e32 v136, vcc, 0x2f5b8000, v192
	global_load_dwordx4 v[128:131], v[128:129], off
	s_nop 0
	global_load_dwordx4 v[132:135], v[132:133], off
	v_addc_co_u32_e32 v137, vcc, 0, v193, vcc
	v_add_co_u32_e32 v140, vcc, 0x2f5b8000, v190
	s_nop 1
	v_addc_co_u32_e32 v141, vcc, 0, v191, vcc
	global_load_dwordx4 v[136:139], v[136:137], off
	s_nop 0
	global_load_dwordx4 v[140:143], v[140:141], off

; __global__ void __launch_bounds__(NTHR, 2) mega(Params p) {
;     extern __shared__ __attribute__((aligned(16))) unsigned char shm[];
	.amdhsa_kernel _Z4mega6Params
		.amdhsa_group_segment_fixed_size 0
		.amdhsa_private_segment_fixed_size 0
		.amdhsa_kernarg_size 464
		.amdhsa_user_sgpr_count 2
		.amdhsa_user_sgpr_dispatch_ptr 0
		.amdhsa_user_sgpr_queue_ptr 0
		.amdhsa_user_sgpr_kernarg_segment_ptr 1
		.amdhsa_user_sgpr_dispatch_id 0
		.amdhsa_user_sgpr_kernarg_preload_length 0
		.amdhsa_user_sgpr_kernarg_preload_offset 0
		.amdhsa_user_sgpr_private_segment_size 0
		.amdhsa_uses_dynamic_stack 0
		.amdhsa_enable_private_segment 0
		.amdhsa_system_sgpr_workgroup_id_x 1
		.amdhsa_system_sgpr_workgroup_id_y 0
		.amdhsa_system_sgpr_workgroup_id_z 0
		.amdhsa_system_sgpr_workgroup_info 0
		.amdhsa_system_vgpr_workitem_id 2
		.amdhsa_next_free_vgpr 256
		.amdhsa_next_free_sgpr 98
		.amdhsa_accum_offset 256
		.amdhsa_reserve_vcc 1
		.amdhsa_float_round_mode_32 0
		.amdhsa_float_round_mode_16_64 0
		.amdhsa_float_denorm_mode_32 3
		.amdhsa_float_denorm_mode_16_64 3
		.amdhsa_dx10_clamp 1
		.amdhsa_ieee_mode 1
		.amdhsa_fp16_overflow 0
		.amdhsa_tg_split 0
		.amdhsa_exception_fp_ieee_invalid_op 0
		.amdhsa_exception_fp_denorm_src 0
		.amdhsa_exception_fp_ieee_div_zero 0
		.amdhsa_exception_fp_ieee_overflow 0
		.amdhsa_exception_fp_ieee_underflow 0
		.amdhsa_exception_fp_ieee_inexact 0
		.amdhsa_exception_int_div_zero 0
	.end_amdhsa_kernel

amdhsa.kernels:
  - .agpr_count:     0
    .args:
      - .offset:         0
        .size:           208
        .value_kind:     by_value
      - .offset:         208
        .size:           4
        .value_kind:     hidden_block_count_x
      - .offset:         212
        .size:           4
        .value_kind:     hidden_block_count_y
      - .offset:         216
        .size:           4
        .value_kind:     hidden_block_count_z
      - .offset:         220
        .size:           2
        .value_kind:     hidden_group_size_x
      - .offset:         222
        .size:           2
        .value_kind:     hidden_group_size_y
      - .offset:         224
        .size:           2
        .value_kind:     hidden_group_size_z
      - .offset:         226
        .size:           2
        .value_kind:     hidden_remainder_x
      - .offset:         228
        .size:           2
        .value_kind:     hidden_remainder_y
      - .offset:         230
        .size:           2
        .value_kind:     hidden_remainder_z
      - .offset:         248
        .size:           8
        .value_kind:     hidden_global_offset_x
      - .offset:         256
        .size:           8
        .value_kind:     hidden_global_offset_y
      - .offset:         264
        .size:           8
        .value_kind:     hidden_global_offset_z
      - .offset:         272
        .size:           2
        .value_kind:     hidden_grid_dims
      - .offset:         296
        .size:           8
        .value_kind:     hidden_multigrid_sync_arg
      - .offset:         328
        .size:           4
        .value_kind:     hidden_dynamic_lds_size
    .group_segment_fixed_size: 0
    .kernarg_segment_align: 8
    .kernarg_segment_size: 464
    .language:       OpenCL C
    .language_version:
      - 2
      - 0
    .max_flat_workgroup_size: 512
    .name:           _Z4mega6Params
    .private_segment_fixed_size: 0
    .sgpr_count:     104
    .sgpr_spill_count: 6
    .symbol:         _Z4mega6Params.kd
    .uniform_work_group_size: 1
    .uses_dynamic_stack: false
    .vgpr_count:     256
    .vgpr_spill_count: 0
    .wavefront_size: 64
